# v35: P3 also issues the next unit's slot-0 LDS-DMA pieces at the start of the EpiIn epilogue (plain/gate tiles); slot-2 first-iteration wait relaxed to vmcnt(24)
# speedup vs baseline: 1.0031x; 1.0000x over previous
; template <class Epi>
; __device__ __forceinline__ void gemm_phase(LAS unsigned char* lds, const Gemm g, const Sched& S, const Epi& E) {
;     ...
;     for (;;) {
;         const bool has_next = S.next(ui + 1, nxt);
;         const char* nA = has_next ? (const char*)g.A + (size_t)nxt.pm * tstepA + (size_t)nxt.part * g.koff * 2 : cA; const char* nB = has_next ? (const char*)g.Bt + (size_t)nxt.pn * tstepB + (size_t)nxt.part * g.koff * 2 : cB;
.LBB0_813:
	s_mov_b64 s[0:1], 0
	s_sub_i32 s99, s10, 12
	s_cmp_lt_u32 s99, 5
	s_cselect_b32 s98, 2, 3
	s_cmp_eq_u32 s10, 26
	s_cselect_b32 s98, 0, s98

; #define PG8_STAGE(bufoff, gbase, voff) do { _Pragma("unroll") for (int _i = 0; _i < 2; ++_i) \
;         __builtin_amdgcn_global_load_lds((const unsigned*)((const char*)(gbase) + (voff)[_i]), (LAS unsigned*)(lds + (bufoff) + ldsw + _i * 8192), 16, 0, 0); } while (0)
; #define PG8_LDA(dst, b, h) do { _Pragma("unroll") for (int m = 0; m < 4; ++m) _Pragma("unroll") for (int k = 0; k < 2; ++k) dst[m][k] = *(const LAS bf16x8*)(lds + PG8_SA(b, h) + aoff + m * 2048 + k * 1024); } while (0)
; #define PG8_LDB(dst, b, h) do { _Pragma("unroll") for (int n = 0; n < 2; ++n) _Pragma("unroll") for (int k = 0; k < 2; ++k) dst[n][k] = *(const LAS bf16x8*)(lds + PG8_SB(b, h) + boff + n * 2048 + k * 1024); } while (0)
; #define PG8_SCHED __builtin_amdgcn_sched_barrier(0)
; template <class Epi>
; __device__ __forceinline__ void gemm_phase(LAS unsigned char* lds, const Gemm g, const Sched& S, const Epi& E) {
;     ...
;             PG8_LDB(B0, 0, 0); PG8_LDB(B1, 0, 1); PG8_SCHED; PG8_LDA(At, 0, 0); PG8_STAGE(PG8_SA(1, 1), a1 + hstepA, voffA);
.LBB0_822:
	ds_read_b128 v[130:133], v210
	ds_read_b128 v[134:137], v210 offset:1024
	ds_read_b128 v[138:141], v210 offset:2048
	ds_read_b128 v[142:145], v210 offset:3072
	ds_read_b128 v[146:149], v211
	ds_read_b128 v[150:153], v211 offset:1024
	ds_read_b128 v[180:183], v211 offset:2048
	ds_read_b128 v[184:187], v211 offset:3072
	s_add_u32 s6, s4, 0xfffc0080
	s_addc_u32 s7, s5, -1
	s_cmp_eq_u32 s77, 12
	s_cselect_b32 s21, s25, s7
	s_cselect_b32 s20, s55, s6
	s_cselect_b32 s7, s72, s75
	s_cselect_b32 s6, s73, s74
	v_lshl_add_u64 v[240:241], s[4:5], 0, v[172:173]
	s_add_i32 m0, s11, 0xc000
	ds_read_b128 v[188:191], v212
	ds_read_b128 v[192:195], v212 offset:1024
	ds_read_b128 v[216:219], v212 offset:2048
	ds_read_b128 v[220:223], v212 offset:3072
	ds_read_b128 v[224:227], v212 offset:4096
	ds_read_b128 v[228:231], v212 offset:5120
	ds_read_b128 v[232:235], v212 offset:6144
	ds_read_b128 v[236:239], v212 offset:7168
	s_cmp_eq_u32 s98, 3
	s_cbranch_scc1 .Lpi_p3_s
	global_load_lds_dwordx4 v[240:241], off
	v_lshl_add_u64 v[240:241], s[4:5], 0, v[174:175]
	s_add_i32 m0, s11, 0xe000
	s_nop 0
	global_load_lds_dwordx4 v[240:241], off
.Lpi_p3_s:
	s_cmp_eq_u32 s98, 0
	s_cbranch_scc1 .Lrx_p3_0_n
	s_sub_u32 s98, s98, 1
	s_waitcnt vmcnt(24)
	s_branch .Lrx_p3_0_j

; #define PG8_STAGE(bufoff, gbase, voff) do { _Pragma("unroll") for (int _i = 0; _i < 2; ++_i) \
;         __builtin_amdgcn_global_load_lds((const unsigned*)((const char*)(gbase) + (voff)[_i]), (LAS unsigned*)(lds + (bufoff) + ldsw + _i * 8192), 16, 0, 0); } while (0)
; #define PG8_LDA(dst, b, h) do { _Pragma("unroll") for (int m = 0; m < 4; ++m) _Pragma("unroll") for (int k = 0; k < 2; ++k) dst[m][k] = *(const LAS bf16x8*)(lds + PG8_SA(b, h) + aoff + m * 2048 + k * 1024); } while (0)
; #define PG8_LDB(dst, b, h) do { _Pragma("unroll") for (int n = 0; n < 2; ++n) _Pragma("unroll") for (int k = 0; k < 2; ++k) dst[n][k] = *(const LAS bf16x8*)(lds + PG8_SB(b, h) + boff + n * 2048 + k * 1024); } while (0)
; #define PG8_SCHED __builtin_amdgcn_sched_barrier(0)
; template <class Epi>
; __device__ __forceinline__ void gemm_phase(LAS unsigned char* lds, const Gemm g, const Sched& S, const Epi& E) {
;     ...
;             PG8_LDB(B0, 1, 0); PG8_LDB(B1, 1, 1); PG8_SCHED; PG8_LDA(At, 1, 0); PG8_STAGE(PG8_SA(0, 1), a2 + hstepA, voffA);
.Lcz_p3_1_j:
	s_setprio 0
	s_barrier
	s_add_i32 s82, 0, 0x18000
	s_add_i32 s83, 0, 0x1c000
	v_add_u32_e32 v142, s82, v196
	v_add_u32_e32 v162, s83, v196
	ds_read_b128 v[130:133], v142
	ds_read_b128 v[134:137], v142 offset:1024
	ds_read_b128 v[138:141], v142 offset:2048
	ds_read_b128 v[142:145], v142 offset:3072
	ds_read_b128 v[146:149], v162
	ds_read_b128 v[150:153], v162 offset:1024
	ds_read_b128 v[180:183], v162 offset:2048
	ds_read_b128 v[184:187], v162 offset:3072
	s_add_u32 s20, s20, 0x40000
	s_addc_u32 s21, s21, 0
	s_mov_b32 m0, s79
	v_lshl_add_u64 v[248:249], s[20:21], 0, v[154:155]
	ds_read_b128 v[188:191], v212 offset:32768
	ds_read_b128 v[192:195], v212 offset:33792
	ds_read_b128 v[216:219], v212 offset:34816
	ds_read_b128 v[220:223], v212 offset:35840
	ds_read_b128 v[224:227], v212 offset:36864
	ds_read_b128 v[228:231], v212 offset:37888
	ds_read_b128 v[232:235], v212 offset:38912
	ds_read_b128 v[236:239], v212 offset:39936
	global_load_lds_dwordx4 v[248:249], off
	v_lshl_add_u64 v[248:249], s[20:21], 0, v[158:159]
	s_mov_b32 m0, s18
	s_nop 0
	global_load_lds_dwordx4 v[248:249], off
	s_cmp_eq_u32 s98, 0
	s_cbranch_scc1 .Lrx_p3_2_n
	s_sub_u32 s98, s98, 1
	s_waitcnt vmcnt(24)
	s_branch .Lrx_p3_2_j

; #define LAS __attribute__((address_space(3)))
; __device__ __forceinline__ float fast_exp(float x) { return __builtin_amdgcn_exp2f(x * LOG2E); }
; #define PG8_WAIT_V(n) asm volatile("s_waitcnt vmcnt(" #n ")" ::: "memory")
; template <class Epi>
; __device__ __forceinline__ void gemm_phase(LAS unsigned char* lds, const Gemm g, const Sched& S, const Epi& E) {
;     ...
;             PG8_LDB(B0, 1, 0); PG8_LDB(B1, 1, 1); PG8_SCHED; PG8_LDA(At, 1, 0); PG8_STAGE(PG8_SA(0, 1), a2 + hstepA, voffA);
;             PG8_WAIT_V(8); PG8_WAIT_L(0); PG8_BAR; PG8_MMA(0, 0, At, B0); PG8_MMA(0, 1, At, B1); PG8_BAR; PG8_SCHED;
;             PG8_LDA(At, 1, 1); PG8_STAGE(PG8_SB(1, 0), b3, voffB); PG8_STAGE(PG8_SB(1, 1), b3 + hstepB, voffB); PG8_STAGE(PG8_SA(1, 0), a3, voffA);
;             PG8_WAIT_V(8); PG8_WAIT_L(0); PG8_BAR; PG8_MMA(1, 0, At, B0); PG8_MMA(1, 1, At, B1); PG8_BAR; PG8_SCHED;
;         }
;     __device__ __forceinline__ void operator()(const Acc& acc, const Unit& u, int wr, int wc, int fr, int fq) const {
;         const int pn = u.pn, cpos = wc * 32 + 8 * fq;
;         const LAS float* rt = rtab + u.idx * 256 + wr * 64 + fr;
;         if (pn >= 18 && pn < 26) {
;             EPI_IN_ROWS({
;                 bf16_t* dst = G + (size_t)row * 2048 + (pn - 18) * 128 + cpos;
;                 f32x4 r0, r1, s0, s1;
;                 _Pragma("unroll") for (int e = 0; e < 4; ++e) {
;                     const float pa0 = 1.f + fast_exp(fminf(-v[0][0][e], 40.f)), pa1 = 1.f + fast_exp(fminf(-v[0][1][e], 40.f)), pb0 = 1.f + fast_exp(fminf(-v[1][0][e], 40.f)), pb1 = 1.f + fast_exp(fminf(-v[1][1][e], 40.f));
;                     const float q0 = __builtin_amdgcn_rcpf(pa0 * pb0), q1 = __builtin_amdgcn_rcpf(pa1 * pb1);
;                     s0[e] = pa0 * q0; s1[e] = pa1 * q1;
;                     r0[e] = pb0 * (pb0 * q0); r1[e] = pb1 * (pb1 * q1);
;                 }
;                 *(u32x4*)dst = pack8(r0, r1); *(u32x4*)(dst + 1024) = pack8(s0, s1);
;             })
;         } else if (pn < 12 || pn == 17) {
;             bf16_t* dst0; size_t ld; float sc = 1.f;
;             if (pn < 4) { dst0 = QK + pn * 256; ld = 1024; if (pn < 2) sc = 0.08838834764831845f; }
;             else if (pn < 8) { dst0 = V + (pn - 4) * 256; ld = 1024; }
;             else if (pn < 12) { dst0 = AB + (pn - 8) * 256; ld = 2048; }
;             else { dst0 = SKV + 256; ld = 512; }
.Lrx_p3_2_j:
	s_waitcnt lgkmcnt(0)
	s_barrier
	s_setprio 1
	s_waitcnt lgkmcnt(0)
	v_mfma_f32_16x16x32_bf16 v[126:129], v[130:133], v[188:191], v[126:129]
	v_mfma_f32_16x16x32_bf16 v[122:125], v[138:141], v[188:191], v[122:125]
	v_mfma_f32_16x16x32_bf16 v[110:113], v[130:133], v[216:219], v[110:113]
	v_mfma_f32_16x16x32_bf16 v[106:109], v[138:141], v[216:219], v[106:109]
	v_mfma_f32_16x16x32_bf16 v[94:97], v[130:133], v[224:227], v[94:97]
	v_mfma_f32_16x16x32_bf16 v[90:93], v[138:141], v[224:227], v[90:93]
	v_mfma_f32_16x16x32_bf16 v[78:81], v[130:133], v[232:235], v[78:81]
	v_mfma_f32_16x16x32_bf16 v[74:77], v[138:141], v[232:235], v[74:77]
	v_mfma_f32_16x16x32_bf16 v[126:129], v[134:137], v[192:195], v[126:129]
	v_mfma_f32_16x16x32_bf16 v[122:125], v[142:145], v[192:195], v[122:125]
	v_mfma_f32_16x16x32_bf16 v[110:113], v[134:137], v[220:223], v[110:113]
	v_mfma_f32_16x16x32_bf16 v[106:109], v[142:145], v[220:223], v[106:109]
	v_mfma_f32_16x16x32_bf16 v[94:97], v[134:137], v[228:231], v[94:97]
	v_mfma_f32_16x16x32_bf16 v[90:93], v[142:145], v[228:231], v[90:93]
	v_mfma_f32_16x16x32_bf16 v[78:81], v[134:137], v[236:239], v[78:81]
	v_mfma_f32_16x16x32_bf16 v[74:77], v[142:145], v[236:239], v[74:77]
	s_setprio 0
	s_setprio 1
	v_mfma_f32_16x16x32_bf16 v[118:121], v[146:149], v[188:191], v[118:121]
	v_mfma_f32_16x16x32_bf16 v[114:117], v[180:183], v[188:191], v[114:117]
	v_mfma_f32_16x16x32_bf16 v[102:105], v[146:149], v[216:219], v[102:105]
	v_mfma_f32_16x16x32_bf16 v[98:101], v[180:183], v[216:219], v[98:101]
	v_mfma_f32_16x16x32_bf16 v[86:89], v[146:149], v[224:227], v[86:89]
	v_mfma_f32_16x16x32_bf16 v[82:85], v[180:183], v[224:227], v[82:85]
	v_mfma_f32_16x16x32_bf16 v[70:73], v[146:149], v[232:235], v[70:73]
	v_mfma_f32_16x16x32_bf16 v[66:69], v[180:183], v[232:235], v[66:69]
	v_mfma_f32_16x16x32_bf16 v[118:121], v[150:153], v[192:195], v[118:121]
	v_mfma_f32_16x16x32_bf16 v[114:117], v[184:187], v[192:195], v[114:117]
	v_mfma_f32_16x16x32_bf16 v[102:105], v[150:153], v[220:223], v[102:105]
	v_mfma_f32_16x16x32_bf16 v[98:101], v[184:187], v[220:223], v[98:101]
	v_mfma_f32_16x16x32_bf16 v[86:89], v[150:153], v[228:231], v[86:89]
	v_mfma_f32_16x16x32_bf16 v[82:85], v[184:187], v[228:231], v[82:85]
	v_mfma_f32_16x16x32_bf16 v[70:73], v[150:153], v[236:239], v[70:73]
	v_mfma_f32_16x16x32_bf16 v[66:69], v[184:187], v[236:239], v[66:69]
	s_setprio 0
	s_barrier
	s_add_i32 s20, s82, s78
	v_lshl_add_u64 v[240:241], v[240:241], 0, s[26:27]
	s_mov_b32 m0, s20
	ds_read_b128 v[188:191], v212 offset:49152
	ds_read_b128 v[192:195], v212 offset:50176
	ds_read_b128 v[216:219], v212 offset:51200
	ds_read_b128 v[220:223], v212 offset:52224
	ds_read_b128 v[224:227], v212 offset:53248
	ds_read_b128 v[228:231], v212 offset:54272
	ds_read_b128 v[232:235], v212 offset:55296
	ds_read_b128 v[236:239], v212 offset:56320
	global_load_lds_dwordx4 v[240:241], off
	s_add_i32 m0, s20, 0x2000
	s_add_u32 s6, s6, 0x40080
	v_lshl_add_u64 v[240:241], v[242:243], 0, s[26:27]
	s_addc_u32 s7, s7, 0
	s_add_i32 s20, s83, s78
	global_load_lds_dwordx4 v[240:241], off
	v_lshl_add_u64 v[240:241], s[6:7], 0, v[156:157]
	s_mov_b32 m0, s20
	s_nop 0
	global_load_lds_dwordx4 v[240:241], off
	v_lshl_add_u64 v[240:241], s[6:7], 0, v[160:161]
	s_add_i32 m0, s20, 0x2000
	s_nop 0
	global_load_lds_dwordx4 v[240:241], off
	v_lshl_add_u64 v[240:241], v[244:245], 0, s[26:27]
	s_mov_b32 m0, s84
	s_nop 0
	global_load_lds_dwordx4 v[240:241], off
	v_lshl_add_u64 v[240:241], v[246:247], 0, s[26:27]
	s_mov_b32 m0, s85
	s_nop 0
	global_load_lds_dwordx4 v[240:241], off
	s_waitcnt vmcnt(8)
	s_waitcnt lgkmcnt(0)
	s_barrier
	s_setprio 1
	s_waitcnt lgkmcnt(0)
	v_mfma_f32_16x16x32_bf16 v[62:65], v[130:133], v[188:191], v[62:65]
	v_mfma_f32_16x16x32_bf16 v[58:61], v[138:141], v[188:191], v[58:61]
	v_mfma_f32_16x16x32_bf16 v[46:49], v[130:133], v[216:219], v[46:49]
	v_mfma_f32_16x16x32_bf16 v[42:45], v[138:141], v[216:219], v[42:45]
	v_mfma_f32_16x16x32_bf16 v[30:33], v[130:133], v[224:227], v[30:33]
	v_mfma_f32_16x16x32_bf16 v[26:29], v[138:141], v[224:227], v[26:29]
	v_mfma_f32_16x16x32_bf16 v[14:17], v[130:133], v[232:235], v[14:17]
	v_mfma_f32_16x16x32_bf16 v[10:13], v[138:141], v[232:235], v[10:13]
	v_mfma_f32_16x16x32_bf16 v[62:65], v[134:137], v[192:195], v[62:65]
	v_mfma_f32_16x16x32_bf16 v[58:61], v[142:145], v[192:195], v[58:61]
	v_mfma_f32_16x16x32_bf16 v[46:49], v[134:137], v[220:223], v[46:49]
	v_mfma_f32_16x16x32_bf16 v[42:45], v[142:145], v[220:223], v[42:45]
	v_mfma_f32_16x16x32_bf16 v[30:33], v[134:137], v[228:231], v[30:33]
	v_mfma_f32_16x16x32_bf16 v[26:29], v[142:145], v[228:231], v[26:29]
	v_mfma_f32_16x16x32_bf16 v[14:17], v[134:137], v[236:239], v[14:17]
	v_mfma_f32_16x16x32_bf16 v[10:13], v[142:145], v[236:239], v[10:13]
	s_setprio 0
	s_setprio 1
	v_mfma_f32_16x16x32_bf16 v[54:57], v[146:149], v[188:191], v[54:57]
	v_mfma_f32_16x16x32_bf16 v[50:53], v[180:183], v[188:191], v[50:53]
	v_mfma_f32_16x16x32_bf16 v[38:41], v[146:149], v[216:219], v[38:41]
	v_mfma_f32_16x16x32_bf16 v[34:37], v[180:183], v[216:219], v[34:37]
	v_mfma_f32_16x16x32_bf16 v[22:25], v[146:149], v[224:227], v[22:25]
	v_mfma_f32_16x16x32_bf16 v[18:21], v[180:183], v[224:227], v[18:21]
	v_mfma_f32_16x16x32_bf16 v[6:9], v[146:149], v[232:235], v[6:9]
	v_mfma_f32_16x16x32_bf16 v[2:5], v[180:183], v[232:235], v[2:5]
	v_mfma_f32_16x16x32_bf16 v[54:57], v[150:153], v[192:195], v[54:57]
	v_mfma_f32_16x16x32_bf16 v[50:53], v[184:187], v[192:195], v[50:53]
	v_mfma_f32_16x16x32_bf16 v[38:41], v[150:153], v[220:223], v[38:41]
	v_mfma_f32_16x16x32_bf16 v[34:37], v[184:187], v[220:223], v[34:37]
	v_mfma_f32_16x16x32_bf16 v[22:25], v[150:153], v[228:231], v[22:25]
	v_mfma_f32_16x16x32_bf16 v[18:21], v[184:187], v[228:231], v[18:21]
	v_mfma_f32_16x16x32_bf16 v[6:9], v[150:153], v[236:239], v[6:9]
	v_mfma_f32_16x16x32_bf16 v[2:5], v[184:187], v[236:239], v[2:5]
	s_setprio 0
	s_barrier
	s_add_i32 s77, s77, 2
	s_add_u32 s4, s4, 0x100
	s_addc_u32 s5, s5, 0
	s_add_u32 s74, s74, 0x100
	s_addc_u32 s75, s75, 0
	s_cmp_gt_u32 s77, 13
	s_cbranch_scc0 .LBB0_822
	s_and_b64 vcc, exec, s[28:29]
	s_cbranch_vccz .LBB0_825
	s_barrier
.LBB0_825:
	s_cmp_eq_u32 s10, 26
	s_cbranch_scc1 .Lpi_p3_e
	s_sub_i32 s100, s10, 12
	s_cmp_lt_u32 s100, 5
	s_cbranch_scc1 .Lpi_p3_e
	s_cmp_eq_u64 s[0:1], 0
	s_cbranch_scc1 .Lpi_p3_e
	s_add_u32 s100, s42, 0x40080
	s_addc_u32 s101, s43, 0
	v_lshl_add_u64 v[240:241], s[100:101], 0, v[172:173]
	s_add_i32 m0, s11, 0xc000
	s_nop 0
	global_load_lds_dwordx4 v[240:241], off
	v_lshl_add_u64 v[240:241], s[100:101], 0, v[174:175]
	s_add_i32 m0, s11, 0xe000
	s_nop 0
	global_load_lds_dwordx4 v[240:241], off
